# gslayout_v105 + HGRN2 head-output stores widened: v_permlane16_swap pairs then one dwordx4 per k-tile, each store covers a whole 1 KiB obuf piece
# speedup vs baseline: 1.0145x; 1.0145x over previous
.LBB0_1094:
	s_ashr_i32 s4, s70, 2
	v_and_b32_e32 v0, 63, v181
	s_cmpk_gt_i32 s4, 0x1ff
	s_cselect_b64 s[0:1], -1, 0
	v_ashrrev_i32_e32 v1, 6, v181
	s_cmpk_lt_i32 s4, 0x200
	s_cselect_b64 s[24:25], -1, 0
	v_cmp_gt_i32_e32 vcc, 1, v1
	s_nop 1
	s_or_b64 s[42:43], s[24:25], vcc
	s_lshl_b32 s5, s4, 4
	s_addk_i32 s5, 0x6000
	s_lshl_b32 s6, s4, 6
	s_and_b64 s[0:1], s[0:1], exec
	s_cselect_b32 s0, s5, s6
	s_and_b32 s5, s70, 0xfffffe00
	s_bfe_u32 s6, s70, 0x70002
	s_and_b32 s1, s60, 0x180
	s_or_b32 s5, s6, s5
	s_or_b32 s5, s5, s1
	s_lshr_b32 s98, s4, 2
	s_lshl_b32 s98, s98, 21
	s_and_b32 s99, s4, 3
	s_lshl_b32 s99, s99, 14
	s_or_b32 s98, s98, s99
	s_lshl_b32 s99, s1, 11
	s_add_u32 s98, s98, s99
	s_add_u32 s98, s98, 0x100000
	s_cmpk_lt_i32 s4, 0x200
	s_cselect_b64 s[100:101], -1, 0
	s_cselect_b32 s99, 0x10000, 64
	s_cmpk_lt_i32 s4, 0x200
	s_cselect_b32 s4, s5, s70
	s_ashr_i32 s5, s4, 31
	s_lshl_b64 s[24:25], s[4:5], 14
	s_add_u32 s30, s46, s24
	s_addc_u32 s31, s47, s25
	s_add_u32 s24, s56, s24
	s_addc_u32 s25, s57, s25
	s_lshl_b64 s[4:5], s[4:5], 15
	s_add_u32 s4, s58, s4
	s_addc_u32 s5, s59, s5
	v_and_b32_e32 v2, 15, v181
	v_bfe_u32 v3, v181, 4, 2
	v_lshlrev_b32_e32 v4, 3, v0
	v_lshl_add_u32 v4, v1, 12, v4
	v_lshl_add_u32 v5, v1, 4, v2
	v_lshlrev_b32_e32 v5, 8, v5
	v_lshl_add_u32 v5, v3, 4, v5
	v_lshlrev_b32_e32 v6, 4, v181
	v_add_u32_e32 v7, 0x1000, v6
	v_add_u32_e32 v8, 0x2000, v6
	v_add_u32_e32 v9, 0x3000, v6
	v_add_u32_e32 v10, 0x4000, v6
	v_add_u32_e32 v11, 0x5000, v6
	v_add_u32_e32 v12, 0x6000, v6
	v_add_u32_e32 v13, 0x7000, v6
	v_lshrrev_b32_e32 v16, 4, v181
	v_mul_u32_u24_e32 v16, 272, v16
	v_lshl_add_u32 v16, v2, 4, v16
	v_mul_u32_u24_e32 v233, 272, v2
	v_lshl_add_u32 v233, v3, 4, v233
	v_lshl_add_u32 v14, v1, 4, s0
	v_add_u32_e32 v14, v14, v2
	v_lshlrev_b32_e32 v14, 13, v14
	v_lshlrev_b32_e32 v15, 3, v3
	v_add_u32_e32 v14, v14, v15
	s_lshl_b32 s6, s1, 1
	s_add_i32 s6, s6, 0x400
	v_add_u32_e32 v232, s6, v14
	v_add_u32_e32 v14, 0x1800, v232
	v_lshrrev_b32_e32 v234, 1, v1
	v_lshlrev_b32_e32 v234, 13, v234
	v_and_b32_e32 v235, 1, v1
	v_lshl_or_b32 v234, v235, 10, v234
	v_lshl_or_b32 v234, v2, 6, v234
	v_lshrrev_b32_e32 v235, 1, v3
	v_bfe_u32 v236, v2, 1, 2
	v_xor_b32_e32 v235, v235, v236
	v_lshl_or_b32 v234, v235, 4, v234
	v_and_b32_e32 v235, 1, v3
	v_lshl_or_b32 v234, v235, 3, v234
	v_add_u32_e32 v234, s98, v234
	v_cndmask_b32_e64 v232, v232, v234, s[100:101]
	v_xor_b32_e32 v234, 32, v232
	v_and_b32_e32 v235, 1, v3
	v_lshlrev_b32_e32 v236, 3, v235
	v_sub_u32_e32 v232, v232, v236
	v_lshlrev_b32_e32 v236, 5, v235
	v_xor_b32_e32 v232, v232, v236
	global_load_dwordx2 v[62:63], v4, s[30:31]
	global_load_dwordx2 v[64:65], v4, s[30:31] offset:512
	global_load_dwordx2 v[66:67], v4, s[30:31] offset:1024
	global_load_dwordx2 v[68:69], v4, s[30:31] offset:1536
	global_load_dwordx2 v[70:71], v4, s[30:31] offset:2048
	global_load_dwordx2 v[72:73], v4, s[30:31] offset:2560
	global_load_dwordx2 v[74:75], v4, s[30:31] offset:3072
	global_load_dwordx2 v[76:77], v4, s[30:31] offset:3584
	global_load_dwordx4 v[46:49], v5, s[24:25]
	global_load_dwordx4 v[50:53], v5, s[24:25] offset:64
	global_load_dwordx4 v[54:57], v5, s[24:25] offset:128
	global_load_dwordx4 v[58:61], v5, s[24:25] offset:192
	global_load_dwordx2 v[216:217], v14, s[20:21]
	global_load_dwordx2 v[218:219], v14, s[20:21] offset:32
	global_load_dwordx2 v[220:221], v14, s[20:21] offset:64
	global_load_dwordx2 v[222:223], v14, s[20:21] offset:96
	global_load_dwordx2 v[224:225], v14, s[20:21] offset:128
	global_load_dwordx2 v[226:227], v14, s[20:21] offset:160
	global_load_dwordx2 v[228:229], v14, s[20:21] offset:192
	global_load_dwordx2 v[230:231], v14, s[20:21] offset:224
	global_load_dwordx4 v[78:81], v6, s[4:5]
	global_load_dwordx4 v[82:85], v7, s[4:5]
	global_load_dwordx4 v[86:89], v8, s[4:5]
	global_load_dwordx4 v[90:93], v9, s[4:5]
	global_load_dwordx4 v[94:97], v10, s[4:5]
	global_load_dwordx4 v[98:101], v11, s[4:5]
	global_load_dwordx4 v[102:105], v12, s[4:5]
	global_load_dwordx4 v[106:109], v13, s[4:5]
	s_barrier
	s_waitcnt vmcnt(0)
	ds_write_b128 v16, v[78:81]
	ds_write_b128 v16, v[82:85] offset:4352
	ds_write_b128 v16, v[86:89] offset:8704
	ds_write_b128 v16, v[90:93] offset:13056
	ds_write_b128 v16, v[94:97] offset:17408
	ds_write_b128 v16, v[98:101] offset:21760
	ds_write_b128 v16, v[102:105] offset:26112
	ds_write_b128 v16, v[106:109] offset:30464
	s_waitcnt lgkmcnt(0)
	s_barrier
	s_mov_b64 vcc, s[42:43]
	s_and_saveexec_b64 s[42:43], vcc
	s_cbranch_execz .LBB0_1087
	v_lshlrev_b32_e32 v28, 16, v62
	v_and_b32_e32 v29, 0xffff0000, v62
	v_lshlrev_b32_e32 v30, 16, v63
	v_and_b32_e32 v31, 0xffff0000, v63
	v_lshlrev_b32_e32 v24, 16, v64
	v_and_b32_e32 v25, 0xffff0000, v64
	v_lshlrev_b32_e32 v26, 16, v65
	v_and_b32_e32 v27, 0xffff0000, v65
	v_lshlrev_b32_e32 v20, 16, v66
	v_and_b32_e32 v21, 0xffff0000, v66
	v_lshlrev_b32_e32 v22, 16, v67
	v_and_b32_e32 v23, 0xffff0000, v67
	v_lshlrev_b32_e32 v16, 16, v68
	v_and_b32_e32 v17, 0xffff0000, v68
	v_lshlrev_b32_e32 v18, 16, v69
	v_and_b32_e32 v19, 0xffff0000, v69
	v_lshlrev_b32_e32 v12, 16, v70
	v_and_b32_e32 v13, 0xffff0000, v70
	v_lshlrev_b32_e32 v14, 16, v71
	v_and_b32_e32 v15, 0xffff0000, v71
	v_lshlrev_b32_e32 v8, 16, v72
	v_and_b32_e32 v9, 0xffff0000, v72
	v_lshlrev_b32_e32 v10, 16, v73
	v_and_b32_e32 v11, 0xffff0000, v73
	v_lshlrev_b32_e32 v4, 16, v74
	v_and_b32_e32 v5, 0xffff0000, v74
	v_lshlrev_b32_e32 v6, 16, v75
	v_and_b32_e32 v7, 0xffff0000, v75
	v_lshlrev_b32_e32 v0, 16, v76
	v_and_b32_e32 v1, 0xffff0000, v76
	v_lshlrev_b32_e32 v2, 16, v77
	v_and_b32_e32 v3, 0xffff0000, v77
	ds_read_b128 v[78:81], v233 offset:0
	ds_read_b128 v[82:85], v233 offset:4352
	ds_read_b128 v[86:89], v233 offset:8704
	ds_read_b128 v[90:93], v233 offset:13056
	ds_read_b128 v[94:97], v233 offset:17408
	ds_read_b128 v[98:101], v233 offset:21760
	ds_read_b128 v[102:105], v233 offset:26112
	ds_read_b128 v[106:109], v233 offset:30464
	s_waitcnt lgkmcnt(4)
	ds_read_b128 v[110:113], v233 offset:64
	ds_read_b128 v[114:117], v233 offset:4416
	ds_read_b128 v[118:121], v233 offset:8768
	ds_read_b128 v[122:125], v233 offset:13120
	ds_read_b128 v[126:129], v233 offset:17472
	ds_read_b128 v[130:133], v233 offset:21824
	ds_read_b128 v[134:137], v233 offset:26176
	ds_read_b128 v[138:141], v233 offset:30528
	s_waitcnt lgkmcnt(8)
	v_mfma_f32_16x16x32_bf16 v[28:31], v[78:81], v[46:49], v[28:31]
	v_mfma_f32_16x16x32_bf16 v[24:27], v[82:85], v[46:49], v[24:27]
	v_mfma_f32_16x16x32_bf16 v[20:23], v[86:89], v[46:49], v[20:23]
	v_mfma_f32_16x16x32_bf16 v[16:19], v[90:93], v[46:49], v[16:19]
	v_mfma_f32_16x16x32_bf16 v[12:15], v[94:97], v[46:49], v[12:15]
	v_mfma_f32_16x16x32_bf16 v[8:11], v[98:101], v[46:49], v[8:11]
	v_mfma_f32_16x16x32_bf16 v[4:7], v[102:105], v[46:49], v[4:7]
	v_mfma_f32_16x16x32_bf16 v[0:3], v[106:109], v[46:49], v[0:3]
	s_waitcnt lgkmcnt(4)
	ds_read_b128 v[78:81], v233 offset:128
	ds_read_b128 v[82:85], v233 offset:4480
	ds_read_b128 v[86:89], v233 offset:8832
	ds_read_b128 v[90:93], v233 offset:13184
	ds_read_b128 v[94:97], v233 offset:17536
	ds_read_b128 v[98:101], v233 offset:21888
	ds_read_b128 v[102:105], v233 offset:26240
	ds_read_b128 v[106:109], v233 offset:30592
	s_waitcnt lgkmcnt(8)
	v_mfma_f32_16x16x32_bf16 v[28:31], v[110:113], v[50:53], v[28:31]
	v_mfma_f32_16x16x32_bf16 v[24:27], v[114:117], v[50:53], v[24:27]
	v_mfma_f32_16x16x32_bf16 v[20:23], v[118:121], v[50:53], v[20:23]
	v_mfma_f32_16x16x32_bf16 v[16:19], v[122:125], v[50:53], v[16:19]
	v_mfma_f32_16x16x32_bf16 v[12:15], v[126:129], v[50:53], v[12:15]
	v_mfma_f32_16x16x32_bf16 v[8:11], v[130:133], v[50:53], v[8:11]
	v_mfma_f32_16x16x32_bf16 v[4:7], v[134:137], v[50:53], v[4:7]
	v_mfma_f32_16x16x32_bf16 v[0:3], v[138:141], v[50:53], v[0:3]
	s_waitcnt lgkmcnt(4)
	ds_read_b128 v[110:113], v233 offset:192
	ds_read_b128 v[114:117], v233 offset:4544
	ds_read_b128 v[118:121], v233 offset:8896
	ds_read_b128 v[122:125], v233 offset:13248
	ds_read_b128 v[126:129], v233 offset:17600
	ds_read_b128 v[130:133], v233 offset:21952
	ds_read_b128 v[134:137], v233 offset:26304
	ds_read_b128 v[138:141], v233 offset:30656
	s_waitcnt lgkmcnt(8)
	v_mfma_f32_16x16x32_bf16 v[28:31], v[78:81], v[54:57], v[28:31]
	v_mfma_f32_16x16x32_bf16 v[24:27], v[82:85], v[54:57], v[24:27]
	v_mfma_f32_16x16x32_bf16 v[20:23], v[86:89], v[54:57], v[20:23]
	v_mfma_f32_16x16x32_bf16 v[16:19], v[90:93], v[54:57], v[16:19]
	v_mfma_f32_16x16x32_bf16 v[12:15], v[94:97], v[54:57], v[12:15]
	v_mfma_f32_16x16x32_bf16 v[8:11], v[98:101], v[54:57], v[8:11]
	v_mfma_f32_16x16x32_bf16 v[4:7], v[102:105], v[54:57], v[4:7]
	v_mfma_f32_16x16x32_bf16 v[0:3], v[106:109], v[54:57], v[0:3]
	s_waitcnt lgkmcnt(0)
	v_mfma_f32_16x16x32_bf16 v[28:31], v[110:113], v[58:61], v[28:31]
	v_mfma_f32_16x16x32_bf16 v[24:27], v[114:117], v[58:61], v[24:27]
	v_mfma_f32_16x16x32_bf16 v[20:23], v[118:121], v[58:61], v[20:23]
	v_mfma_f32_16x16x32_bf16 v[16:19], v[122:125], v[58:61], v[16:19]
	v_mfma_f32_16x16x32_bf16 v[12:15], v[126:129], v[58:61], v[12:15]
	v_mfma_f32_16x16x32_bf16 v[8:11], v[130:133], v[58:61], v[8:11]
	v_mfma_f32_16x16x32_bf16 v[4:7], v[134:137], v[58:61], v[4:7]
	v_mfma_f32_16x16x32_bf16 v[0:3], v[138:141], v[58:61], v[0:3]
	v_xor_b32_e32 v241, 16, v40
	v_xor_b32_e32 v242, 32, v40
	v_lshlrev_b32_e32 v241, 2, v241
	v_lshlrev_b32_e32 v242, 2, v242
	s_nop 4
	v_mul_f32_e32 v46, v28, v28
	v_fmac_f32_e32 v46, v29, v29
	v_fmac_f32_e32 v46, v30, v30
	v_fmac_f32_e32 v46, v31, v31
	v_fmac_f32_e32 v46, v24, v24
	v_fmac_f32_e32 v46, v25, v25
	v_fmac_f32_e32 v46, v26, v26
	v_fmac_f32_e32 v46, v27, v27
	v_fmac_f32_e32 v46, v20, v20
	v_fmac_f32_e32 v46, v21, v21
	v_fmac_f32_e32 v46, v22, v22
	v_fmac_f32_e32 v46, v23, v23
	v_fmac_f32_e32 v46, v16, v16
	v_fmac_f32_e32 v46, v17, v17
	v_fmac_f32_e32 v46, v18, v18
	v_fmac_f32_e32 v46, v19, v19
	v_fmac_f32_e32 v46, v12, v12
	v_fmac_f32_e32 v46, v13, v13
	v_fmac_f32_e32 v46, v14, v14
	v_fmac_f32_e32 v46, v15, v15
	v_fmac_f32_e32 v46, v8, v8
	v_fmac_f32_e32 v46, v9, v9
	v_fmac_f32_e32 v46, v10, v10
	v_fmac_f32_e32 v46, v11, v11
	v_fmac_f32_e32 v46, v4, v4
	v_fmac_f32_e32 v46, v5, v5
	v_fmac_f32_e32 v46, v6, v6
	v_fmac_f32_e32 v46, v7, v7
	v_fmac_f32_e32 v46, v0, v0
	v_fmac_f32_e32 v46, v1, v1
	v_fmac_f32_e32 v46, v2, v2
	v_fmac_f32_e32 v46, v3, v3
	ds_bpermute_b32 v47, v241, v46
	s_waitcnt lgkmcnt(0)
	v_add_f32_e32 v46, v46, v47
	ds_bpermute_b32 v47, v242, v46
	s_waitcnt lgkmcnt(0)
	v_add_f32_e32 v46, v46, v47
	v_mov_b32_e32 v50, 0x358637bd
	v_fmamk_f32 v46, v46, 0x3c000000, v50
	v_rsq_f32_e32 v46, v46
	v_lshlrev_b32_e32 v48, 16, v216
	v_and_b32_e32 v49, 0xffff0000, v216
	v_lshlrev_b32_e32 v50, 16, v217
	v_and_b32_e32 v51, 0xffff0000, v217
	v_mul_f32_e32 v52, 0xbfb8aa3b, v48
	v_mul_f32_e32 v53, 0xbfb8aa3b, v49
	v_mul_f32_e32 v54, 0xbfb8aa3b, v50
	v_mul_f32_e32 v55, 0xbfb8aa3b, v51
	v_exp_f32_e32 v52, v52
	v_exp_f32_e32 v53, v53
	v_exp_f32_e32 v54, v54
	v_exp_f32_e32 v55, v55
	v_mul_f32_e32 v56, v28, v46
	v_mul_f32_e32 v57, v29, v46
	v_mul_f32_e32 v58, v30, v46
	v_mul_f32_e32 v59, v31, v46
	v_add_f32_e32 v52, 1.0, v52
	v_add_f32_e32 v53, 1.0, v53
	v_add_f32_e32 v54, 1.0, v54
	v_add_f32_e32 v55, 1.0, v55
	v_rcp_f32_e32 v52, v52
	v_rcp_f32_e32 v53, v53
	v_rcp_f32_e32 v54, v54
	v_rcp_f32_e32 v55, v55
	v_mul_f32_e32 v56, v184, v56
	v_mul_f32_e32 v57, v185, v57
	v_mul_f32_e32 v58, v186, v58
	v_mul_f32_e32 v59, v187, v59
	v_mul_f32_e32 v52, v52, v48
	v_mul_f32_e32 v53, v53, v49
	v_mul_f32_e32 v54, v54, v50
	v_mul_f32_e32 v55, v55, v51
	v_mul_f32_e32 v56, v52, v56
	v_mul_f32_e32 v57, v53, v57
	v_mul_f32_e32 v58, v54, v58
	v_mul_f32_e32 v59, v55, v59
	v_cvt_pk_bf16_f32 v60, v56, v57
	v_cvt_pk_bf16_f32 v61, v58, v59
	v_lshlrev_b32_e32 v48, 16, v218
	v_and_b32_e32 v49, 0xffff0000, v218
	v_lshlrev_b32_e32 v50, 16, v219
	v_and_b32_e32 v51, 0xffff0000, v219
	v_mul_f32_e32 v52, 0xbfb8aa3b, v48
	v_mul_f32_e32 v53, 0xbfb8aa3b, v49
	v_mul_f32_e32 v54, 0xbfb8aa3b, v50
	v_mul_f32_e32 v55, 0xbfb8aa3b, v51
	v_exp_f32_e32 v52, v52
	v_exp_f32_e32 v53, v53
	v_exp_f32_e32 v54, v54
	v_exp_f32_e32 v55, v55
	v_mul_f32_e32 v56, v24, v46
	v_mul_f32_e32 v57, v25, v46
	v_mul_f32_e32 v58, v26, v46
	v_mul_f32_e32 v59, v27, v46
	v_add_f32_e32 v52, 1.0, v52
	v_add_f32_e32 v53, 1.0, v53
	v_add_f32_e32 v54, 1.0, v54
	v_add_f32_e32 v55, 1.0, v55
	v_rcp_f32_e32 v52, v52
	v_rcp_f32_e32 v53, v53
	v_rcp_f32_e32 v54, v54
	v_rcp_f32_e32 v55, v55
	v_mul_f32_e32 v56, v188, v56
	v_mul_f32_e32 v57, v189, v57
	v_mul_f32_e32 v58, v190, v58
	v_mul_f32_e32 v59, v191, v59
	v_mul_f32_e32 v52, v52, v48
	v_mul_f32_e32 v53, v53, v49
	v_mul_f32_e32 v54, v54, v50
	v_mul_f32_e32 v55, v55, v51
	v_mul_f32_e32 v56, v52, v56
	v_mul_f32_e32 v57, v53, v57
	v_mul_f32_e32 v58, v54, v58
	v_mul_f32_e32 v59, v55, v59
	v_cvt_pk_bf16_f32 v62, v56, v57
	v_cvt_pk_bf16_f32 v63, v58, v59
	s_mov_b64 s[24:25], s[20:21]
	s_nop 1
	v_permlane16_swap_b32_e32 v60, v62
	v_permlane16_swap_b32_e32 v61, v63
	global_store_dwordx4 v232, v[60:63], s[24:25]
	v_lshlrev_b32_e32 v48, 16, v220
	v_and_b32_e32 v49, 0xffff0000, v220
	v_lshlrev_b32_e32 v50, 16, v221
	v_and_b32_e32 v51, 0xffff0000, v221
	v_mul_f32_e32 v52, 0xbfb8aa3b, v48
	v_mul_f32_e32 v53, 0xbfb8aa3b, v49
	v_mul_f32_e32 v54, 0xbfb8aa3b, v50
	v_mul_f32_e32 v55, 0xbfb8aa3b, v51
	v_exp_f32_e32 v52, v52
	v_exp_f32_e32 v53, v53
	v_exp_f32_e32 v54, v54
	v_exp_f32_e32 v55, v55
	v_mul_f32_e32 v56, v20, v46
	v_mul_f32_e32 v57, v21, v46
	v_mul_f32_e32 v58, v22, v46
	v_mul_f32_e32 v59, v23, v46
	v_add_f32_e32 v52, 1.0, v52
	v_add_f32_e32 v53, 1.0, v53
	v_add_f32_e32 v54, 1.0, v54
	v_add_f32_e32 v55, 1.0, v55
	v_rcp_f32_e32 v52, v52
	v_rcp_f32_e32 v53, v53
	v_rcp_f32_e32 v54, v54
	v_rcp_f32_e32 v55, v55
	v_mul_f32_e32 v56, v192, v56
	v_mul_f32_e32 v57, v193, v57
	v_mul_f32_e32 v58, v194, v58
	v_mul_f32_e32 v59, v195, v59
	v_mul_f32_e32 v52, v52, v48
	v_mul_f32_e32 v53, v53, v49
	v_mul_f32_e32 v54, v54, v50
	v_mul_f32_e32 v55, v55, v51
	v_mul_f32_e32 v56, v52, v56
	v_mul_f32_e32 v57, v53, v57
	v_mul_f32_e32 v58, v54, v58
	v_mul_f32_e32 v59, v55, v59
	v_cvt_pk_bf16_f32 v60, v56, v57
	v_cvt_pk_bf16_f32 v61, v58, v59
	v_lshlrev_b32_e32 v48, 16, v222
	v_and_b32_e32 v49, 0xffff0000, v222
	v_lshlrev_b32_e32 v50, 16, v223
	v_and_b32_e32 v51, 0xffff0000, v223
	v_mul_f32_e32 v52, 0xbfb8aa3b, v48
	v_mul_f32_e32 v53, 0xbfb8aa3b, v49
	v_mul_f32_e32 v54, 0xbfb8aa3b, v50
	v_mul_f32_e32 v55, 0xbfb8aa3b, v51
	v_exp_f32_e32 v52, v52
	v_exp_f32_e32 v53, v53
	v_exp_f32_e32 v54, v54
	v_exp_f32_e32 v55, v55
	v_mul_f32_e32 v56, v16, v46
	v_mul_f32_e32 v57, v17, v46
	v_mul_f32_e32 v58, v18, v46
	v_mul_f32_e32 v59, v19, v46
	v_add_f32_e32 v52, 1.0, v52
	v_add_f32_e32 v53, 1.0, v53
	v_add_f32_e32 v54, 1.0, v54
	v_add_f32_e32 v55, 1.0, v55
	v_rcp_f32_e32 v52, v52
	v_rcp_f32_e32 v53, v53
	v_rcp_f32_e32 v54, v54
	v_rcp_f32_e32 v55, v55
	v_mul_f32_e32 v56, v196, v56
	v_mul_f32_e32 v57, v197, v57
	v_mul_f32_e32 v58, v198, v58
	v_mul_f32_e32 v59, v199, v59
	v_mul_f32_e32 v52, v52, v48
	v_mul_f32_e32 v53, v53, v49
	v_mul_f32_e32 v54, v54, v50
	v_mul_f32_e32 v55, v55, v51
	v_mul_f32_e32 v56, v52, v56
	v_mul_f32_e32 v57, v53, v57
	v_mul_f32_e32 v58, v54, v58
	v_mul_f32_e32 v59, v55, v59
	v_cvt_pk_bf16_f32 v62, v56, v57
	v_cvt_pk_bf16_f32 v63, v58, v59
	s_add_u32 s24, s24, s99
	s_addc_u32 s25, s25, 0
	s_nop 1
	v_permlane16_swap_b32_e32 v60, v62
	v_permlane16_swap_b32_e32 v61, v63
	global_store_dwordx4 v232, v[60:63], s[24:25]
	v_lshlrev_b32_e32 v48, 16, v224
	v_and_b32_e32 v49, 0xffff0000, v224
	v_lshlrev_b32_e32 v50, 16, v225
	v_and_b32_e32 v51, 0xffff0000, v225
	v_mul_f32_e32 v52, 0xbfb8aa3b, v48
	v_mul_f32_e32 v53, 0xbfb8aa3b, v49
	v_mul_f32_e32 v54, 0xbfb8aa3b, v50
	v_mul_f32_e32 v55, 0xbfb8aa3b, v51
	v_exp_f32_e32 v52, v52
	v_exp_f32_e32 v53, v53
	v_exp_f32_e32 v54, v54
	v_exp_f32_e32 v55, v55
	v_mul_f32_e32 v56, v12, v46
	v_mul_f32_e32 v57, v13, v46
	v_mul_f32_e32 v58, v14, v46
	v_mul_f32_e32 v59, v15, v46
	v_add_f32_e32 v52, 1.0, v52
	v_add_f32_e32 v53, 1.0, v53
	v_add_f32_e32 v54, 1.0, v54
	v_add_f32_e32 v55, 1.0, v55
	v_rcp_f32_e32 v52, v52
	v_rcp_f32_e32 v53, v53
	v_rcp_f32_e32 v54, v54
	v_rcp_f32_e32 v55, v55
	v_mul_f32_e32 v56, v200, v56
	v_mul_f32_e32 v57, v201, v57
	v_mul_f32_e32 v58, v202, v58
	v_mul_f32_e32 v59, v203, v59
	v_mul_f32_e32 v52, v52, v48
	v_mul_f32_e32 v53, v53, v49
	v_mul_f32_e32 v54, v54, v50
	v_mul_f32_e32 v55, v55, v51
	v_mul_f32_e32 v56, v52, v56
	v_mul_f32_e32 v57, v53, v57
	v_mul_f32_e32 v58, v54, v58
	v_mul_f32_e32 v59, v55, v59
	v_cvt_pk_bf16_f32 v60, v56, v57
	v_cvt_pk_bf16_f32 v61, v58, v59
	v_lshlrev_b32_e32 v48, 16, v226
	v_and_b32_e32 v49, 0xffff0000, v226
	v_lshlrev_b32_e32 v50, 16, v227
	v_and_b32_e32 v51, 0xffff0000, v227
	v_mul_f32_e32 v52, 0xbfb8aa3b, v48
	v_mul_f32_e32 v53, 0xbfb8aa3b, v49
	v_mul_f32_e32 v54, 0xbfb8aa3b, v50
	v_mul_f32_e32 v55, 0xbfb8aa3b, v51
	v_exp_f32_e32 v52, v52
	v_exp_f32_e32 v53, v53
	v_exp_f32_e32 v54, v54
	v_exp_f32_e32 v55, v55
	v_mul_f32_e32 v56, v8, v46
	v_mul_f32_e32 v57, v9, v46
	v_mul_f32_e32 v58, v10, v46
	v_mul_f32_e32 v59, v11, v46
	v_add_f32_e32 v52, 1.0, v52
	v_add_f32_e32 v53, 1.0, v53
	v_add_f32_e32 v54, 1.0, v54
	v_add_f32_e32 v55, 1.0, v55
	v_rcp_f32_e32 v52, v52
	v_rcp_f32_e32 v53, v53
	v_rcp_f32_e32 v54, v54
	v_rcp_f32_e32 v55, v55
	v_mul_f32_e32 v56, v204, v56
	v_mul_f32_e32 v57, v205, v57
	v_mul_f32_e32 v58, v206, v58
	v_mul_f32_e32 v59, v207, v59
	v_mul_f32_e32 v52, v52, v48
	v_mul_f32_e32 v53, v53, v49
	v_mul_f32_e32 v54, v54, v50
	v_mul_f32_e32 v55, v55, v51
	v_mul_f32_e32 v56, v52, v56
	v_mul_f32_e32 v57, v53, v57
	v_mul_f32_e32 v58, v54, v58
	v_mul_f32_e32 v59, v55, v59
	v_cvt_pk_bf16_f32 v62, v56, v57
	v_cvt_pk_bf16_f32 v63, v58, v59
	s_add_u32 s24, s24, s99
	s_addc_u32 s25, s25, 0
	s_nop 1
	v_permlane16_swap_b32_e32 v60, v62
	v_permlane16_swap_b32_e32 v61, v63
	global_store_dwordx4 v232, v[60:63], s[24:25]
	v_lshlrev_b32_e32 v48, 16, v228
	v_and_b32_e32 v49, 0xffff0000, v228
	v_lshlrev_b32_e32 v50, 16, v229
	v_and_b32_e32 v51, 0xffff0000, v229
	v_mul_f32_e32 v52, 0xbfb8aa3b, v48
	v_mul_f32_e32 v53, 0xbfb8aa3b, v49
	v_mul_f32_e32 v54, 0xbfb8aa3b, v50
	v_mul_f32_e32 v55, 0xbfb8aa3b, v51
	v_exp_f32_e32 v52, v52
	v_exp_f32_e32 v53, v53
	v_exp_f32_e32 v54, v54
	v_exp_f32_e32 v55, v55
	v_mul_f32_e32 v56, v4, v46
	v_mul_f32_e32 v57, v5, v46
	v_mul_f32_e32 v58, v6, v46
	v_mul_f32_e32 v59, v7, v46
	v_add_f32_e32 v52, 1.0, v52
	v_add_f32_e32 v53, 1.0, v53
	v_add_f32_e32 v54, 1.0, v54
	v_add_f32_e32 v55, 1.0, v55
	v_rcp_f32_e32 v52, v52
	v_rcp_f32_e32 v53, v53
	v_rcp_f32_e32 v54, v54
	v_rcp_f32_e32 v55, v55
	v_mul_f32_e32 v56, v208, v56
	v_mul_f32_e32 v57, v209, v57
	v_mul_f32_e32 v58, v210, v58
	v_mul_f32_e32 v59, v211, v59
	v_mul_f32_e32 v52, v52, v48
	v_mul_f32_e32 v53, v53, v49
	v_mul_f32_e32 v54, v54, v50
	v_mul_f32_e32 v55, v55, v51
	v_mul_f32_e32 v56, v52, v56
	v_mul_f32_e32 v57, v53, v57
	v_mul_f32_e32 v58, v54, v58
	v_mul_f32_e32 v59, v55, v59
	v_cvt_pk_bf16_f32 v60, v56, v57
	v_cvt_pk_bf16_f32 v61, v58, v59
	v_lshlrev_b32_e32 v48, 16, v230
	v_and_b32_e32 v49, 0xffff0000, v230
	v_lshlrev_b32_e32 v50, 16, v231
	v_and_b32_e32 v51, 0xffff0000, v231
	v_mul_f32_e32 v52, 0xbfb8aa3b, v48
	v_mul_f32_e32 v53, 0xbfb8aa3b, v49
	v_mul_f32_e32 v54, 0xbfb8aa3b, v50
	v_mul_f32_e32 v55, 0xbfb8aa3b, v51
	v_exp_f32_e32 v52, v52
	v_exp_f32_e32 v53, v53
	v_exp_f32_e32 v54, v54
	v_exp_f32_e32 v55, v55
	v_mul_f32_e32 v56, v0, v46
	v_mul_f32_e32 v57, v1, v46
	v_mul_f32_e32 v58, v2, v46
	v_mul_f32_e32 v59, v3, v46
	v_add_f32_e32 v52, 1.0, v52
	v_add_f32_e32 v53, 1.0, v53
	v_add_f32_e32 v54, 1.0, v54
	v_add_f32_e32 v55, 1.0, v55
	v_rcp_f32_e32 v52, v52
	v_rcp_f32_e32 v53, v53
	v_rcp_f32_e32 v54, v54
	v_rcp_f32_e32 v55, v55
	v_mul_f32_e32 v56, v212, v56
	v_mul_f32_e32 v57, v213, v57
	v_mul_f32_e32 v58, v214, v58
	v_mul_f32_e32 v59, v215, v59
	v_mul_f32_e32 v52, v52, v48
	v_mul_f32_e32 v53, v53, v49
	v_mul_f32_e32 v54, v54, v50
	v_mul_f32_e32 v55, v55, v51
	v_mul_f32_e32 v56, v52, v56
	v_mul_f32_e32 v57, v53, v57
	v_mul_f32_e32 v58, v54, v58
	v_mul_f32_e32 v59, v55, v59
	v_cvt_pk_bf16_f32 v62, v56, v57
	v_cvt_pk_bf16_f32 v63, v58, v59
	s_add_u32 s24, s24, s99
	s_addc_u32 s25, s25, 0
	s_nop 1
	v_permlane16_swap_b32_e32 v60, v62
	v_permlane16_swap_b32_e32 v61, v63
	global_store_dwordx4 v232, v[60:63], s[24:25]
	s_branch .LBB0_1087
